# P6 epilogue v6: per-row (s*-log2e, meansq+eps) pairs computed once per phase, parked per row in LDS and used directly as packed broadcast operands (12 packed ops + 16 transcendentals per row, no per-t
# baseline (speedup 1.0000x reference)
.LBB0_665:
	s_add_u32 s8, s92, 0x7200000
	s_addc_u32 s9, s93, 0
	s_add_u32 s10, s92, 0x10000
	s_addc_u32 s11, s93, 0
	s_lshl_b32 s2, s2, 5
	s_mov_b64 s[12:13], 0x80
	s_and_b32 s18, s2, 0x60
	s_add_i32 m0, s25, 0x18000
	v_lshl_add_u64 v[6:7], v[6:7], 0, s[12:13]
	s_lshl_b32 s15, s14, 13
	s_lshl_b32 s19, s18, 7
	s_waitcnt vmcnt(2)
	s_barrier
	global_load_lds_dwordx4 v[6:7], off
	v_lshl_add_u64 v[4:5], v[4:5], 0, s[12:13]
	s_add_i32 m0, s25, 0x1a000
	s_add_i32 s43, s25, 0x8000
	s_add_i32 s44, s25, 0xa000
	global_load_lds_dwordx4 v[4:5], off
	v_lshl_add_u64 v[0:1], v[0:1], 0, s[12:13]
	s_mov_b32 m0, s43
	s_add_u32 s16, s28, 0x80080
	global_load_lds_dwordx4 v[0:1], off
	v_lshl_add_u64 v[0:1], v[2:3], 0, s[12:13]
	s_mov_b32 m0, s44
	s_addc_u32 s17, s29, 0
	global_load_lds_dwordx4 v[0:1], off
	s_add_i32 m0, s25, 0x1c000
	v_lshl_add_u64 v[0:1], s[16:17], 0, v[134:135]
	global_load_lds_dwordx4 v[0:1], off
	v_lshl_add_u64 v[0:1], s[16:17], 0, v[130:131]
	s_add_i32 m0, s25, 0x1e000
	s_sext_i32_i16 s2, s0
	global_load_lds_dwordx4 v[0:1], off
	v_and_b32_e32 v0, 15, v129
	v_lshlrev_b32_e32 v1, 1, v11
	v_lshlrev_b32_e32 v2, 2, v129
	v_lshlrev_b32_e32 v3, 6, v129
	s_movk_i32 s0, 0x3c0
	v_lshl_or_b32 v148, s14, 6, v0
	v_lshl_or_b32 v0, v0, 6, v1
	v_and_b32_e32 v2, 32, v2
	v_and_or_b32 v1, v3, s0, v1
	v_bitop3_b32 v149, s19, v1, v2 bitop3:0xf6
	v_lshlrev_b32_e32 v1, 9, v129
	v_bitop3_b32 v0, v0, s15, v2 bitop3:0xde
	v_and_b32_e32 v1, 0x70000, v1
	v_lshlrev_b32_e32 v2, 12, v12
	v_or3_b32 v1, v9, v1, v2
	v_add_u32_e32 v138, v1, v10
	v_lshlrev_b32_e32 v1, 5, v8
	s_waitcnt vmcnt(6)
	s_cmpk_lt_u32 s1, 0x100
	v_and_b32_e32 v1, 0xf0000, v1
	s_cselect_b64 s[14:15], -1, 0
	v_or3_b32 v1, v9, v1, v2
	s_add_i32 s46, 0, 0x10000
	s_add_i32 s47, 0, 0x14000
	s_ashr_i32 s45, s96, 31
	v_or_b32_e32 v150, s18, v11
	v_mov_b32_e32 v139, v135
	v_add_u32_e32 v140, v1, v10
	v_mov_b32_e32 v141, v135
	v_mov_b64_e32 v[142:143], 0x580
	v_mov_b64_e32 v[144:145], 0x57f
	v_add_u32_e32 v151, s46, v149
	v_add_u32_e32 v152, s47, v149
	v_add_u32_e32 v153, 0, v0
	v_mov_b32_e32 v154, 0x358637bd
	s_movk_i32 s48, 0x2c00
	s_barrier
	v_lshl_add_u32 v146, s24, 8, v148
	v_lshlrev_b32_e32 v147, 5, v146
	v_add_u32_e32 v254, 0x1000, v147
	v_mov_b32_e32 v252, 0xbfb8aa3b
	global_load_dwordx4 v[156:159], v147, s[10:11]
	global_load_dwordx4 v[160:163], v147, s[10:11] offset:16
	global_load_dwordx4 v[164:167], v147, s[10:11] offset:512
	global_load_dwordx4 v[168:171], v147, s[10:11] offset:528
	global_load_dwordx4 v[172:175], v147, s[10:11] offset:1024
	global_load_dwordx4 v[176:179], v147, s[10:11] offset:1040
	global_load_dwordx4 v[180:183], v147, s[10:11] offset:1536
	global_load_dwordx4 v[184:187], v147, s[10:11] offset:1552
	global_load_dwordx4 v[188:191], v254, s[10:11]
	global_load_dwordx4 v[192:195], v254, s[10:11] offset:16
	global_load_dwordx4 v[196:199], v254, s[10:11] offset:512
	global_load_dwordx4 v[200:203], v254, s[10:11] offset:528
	global_load_dwordx4 v[204:207], v254, s[10:11] offset:1024
	global_load_dwordx4 v[208:211], v254, s[10:11] offset:1040
	global_load_dwordx4 v[212:215], v254, s[10:11] offset:1536
	global_load_dwordx4 v[216:219], v254, s[10:11] offset:1552
	s_waitcnt vmcnt(0)
	v_add_f32_e32 v156, v156, v157
	v_add_f32_e32 v158, v158, v159
	v_add_f32_e32 v160, v160, v161
	v_add_f32_e32 v162, v162, v163
	v_add_f32_e32 v156, v156, v158
	v_add_f32_e32 v160, v160, v162
	v_add_f32_e32 v156, v156, v160
	v_fmamk_f32 v1, v156, 0x3a000000, v154
	v_rsq_f32_e32 v0, v1
	v_add_f32_e32 v164, v164, v165
	v_add_f32_e32 v166, v166, v167
	v_add_f32_e32 v168, v168, v169
	v_add_f32_e32 v170, v170, v171
	v_add_f32_e32 v164, v164, v166
	v_add_f32_e32 v168, v168, v170
	v_add_f32_e32 v164, v164, v168
	v_fmamk_f32 v3, v164, 0x3a000000, v154
	v_rsq_f32_e32 v2, v3
	v_add_f32_e32 v172, v172, v173
	v_add_f32_e32 v174, v174, v175
	v_add_f32_e32 v176, v176, v177
	v_add_f32_e32 v178, v178, v179
	v_add_f32_e32 v172, v172, v174
	v_add_f32_e32 v176, v176, v178
	v_add_f32_e32 v172, v172, v176
	v_fmamk_f32 v5, v172, 0x3a000000, v154
	v_rsq_f32_e32 v4, v5
	v_add_f32_e32 v180, v180, v181
	v_add_f32_e32 v182, v182, v183
	v_add_f32_e32 v184, v184, v185
	v_add_f32_e32 v186, v186, v187
	v_add_f32_e32 v180, v180, v182
	v_add_f32_e32 v184, v184, v186
	v_add_f32_e32 v180, v180, v184
	v_fmamk_f32 v7, v180, 0x3a000000, v154
	v_rsq_f32_e32 v6, v7
	v_add_f32_e32 v188, v188, v189
	v_add_f32_e32 v190, v190, v191
	v_add_f32_e32 v192, v192, v193
	v_add_f32_e32 v194, v194, v195
	v_add_f32_e32 v188, v188, v190
	v_add_f32_e32 v192, v192, v194
	v_add_f32_e32 v188, v188, v192
	v_fmamk_f32 v9, v188, 0x3a000000, v154
	v_rsq_f32_e32 v8, v9
	v_add_f32_e32 v196, v196, v197
	v_add_f32_e32 v198, v198, v199
	v_add_f32_e32 v200, v200, v201
	v_add_f32_e32 v202, v202, v203
	v_add_f32_e32 v196, v196, v198
	v_add_f32_e32 v200, v200, v202
	v_add_f32_e32 v196, v196, v200
	v_fmamk_f32 v11, v196, 0x3a000000, v154
	v_rsq_f32_e32 v10, v11
	v_add_f32_e32 v204, v204, v205
	v_add_f32_e32 v206, v206, v207
	v_add_f32_e32 v208, v208, v209
	v_add_f32_e32 v210, v210, v211
	v_add_f32_e32 v204, v204, v206
	v_add_f32_e32 v208, v208, v210
	v_add_f32_e32 v204, v204, v208
	v_fmamk_f32 v13, v204, 0x3a000000, v154
	v_rsq_f32_e32 v12, v13
	v_add_f32_e32 v212, v212, v213
	v_add_f32_e32 v214, v214, v215
	v_add_f32_e32 v216, v216, v217
	v_add_f32_e32 v218, v218, v219
	v_add_f32_e32 v212, v212, v214
	v_add_f32_e32 v216, v216, v218
	v_add_f32_e32 v212, v212, v216
	v_fmamk_f32 v15, v212, 0x3a000000, v154
	v_rsq_f32_e32 v14, v15
	v_mul_f32_e32 v0, v0, v252
	v_mul_f32_e32 v2, v2, v252
	v_mul_f32_e32 v4, v4, v252
	v_mul_f32_e32 v6, v6, v252
	v_mul_f32_e32 v8, v8, v252
	v_mul_f32_e32 v10, v10, v252
	v_mul_f32_e32 v12, v12, v252
	v_mul_f32_e32 v14, v14, v252
	v_and_b32_e32 v146, 15, v148
	v_lshrrev_b32_e32 v147, 6, v148
	v_lshl_or_b32 v146, v147, 4, v146
	v_lshlrev_b32_e32 v146, 6, v146
	v_add_u32_e32 v146, 0x20000, v146
	ds_write_b128 v146, v[0:3]
	ds_write_b128 v146, v[4:7] offset:16
	ds_write_b128 v146, v[8:11] offset:32
	ds_write_b128 v146, v[12:15] offset:48
	s_branch .LBB0_668

.LBB0_671:
	ds_read_b128 v[156:159], v151
	ds_read_b128 v[160:163], v151 offset:1024
	ds_read_b128 v[164:167], v151 offset:2048
	ds_read_b128 v[168:171], v151 offset:3072
	ds_read_b128 v[172:175], v152
	ds_read_b128 v[176:179], v152 offset:1024
	ds_read_b128 v[180:183], v152 offset:2048
	ds_read_b128 v[184:187], v152 offset:3072
	s_add_u32 s28, s26, 0xfff80080
	s_addc_u32 s29, s27, -1
	s_cmp_eq_u32 s53, 28
	s_cselect_b32 s31, s19, s29
	s_cselect_b32 s30, s49, s28
	s_cselect_b32 s29, s17, s52
	s_cselect_b32 s28, s50, s51
	s_add_u32 s100, s30, 0x80
	s_addc_u32 s101, s31, 0
	s_add_i32 m0, s25, 0xc000
	ds_read_b128 v[188:191], v153
	ds_read_b128 v[192:195], v153 offset:1024
	ds_read_b128 v[196:199], v153 offset:2048
	ds_read_b128 v[200:203], v153 offset:3072
	ds_read_b128 v[204:207], v153 offset:4096
	ds_read_b128 v[208:211], v153 offset:5120
	ds_read_b128 v[212:215], v153 offset:6144
	ds_read_b128 v[216:219], v153 offset:7168
	global_load_lds_dwordx4 v138, s[26:27]
	s_add_i32 m0, s25, 0xe000
	s_nop 0
	global_load_lds_dwordx4 v140, s[26:27]
	s_waitcnt vmcnt(8)
	s_waitcnt lgkmcnt(0)
	s_barrier
	s_waitcnt lgkmcnt(0)
	v_mfma_f32_16x16x32_bf16 v[116:119], v[156:159], v[188:191], v[116:119]
	v_mfma_f32_16x16x32_bf16 v[116:119], v[160:163], v[192:195], v[116:119]
	v_mfma_f32_16x16x32_bf16 v[112:115], v[164:167], v[188:191], v[112:115]
	v_mfma_f32_16x16x32_bf16 v[112:115], v[168:171], v[192:195], v[112:115]
	v_mfma_f32_16x16x32_bf16 v[96:99], v[164:167], v[196:199], v[96:99]
	v_mfma_f32_16x16x32_bf16 v[96:99], v[168:171], v[200:203], v[96:99]
	v_mfma_f32_16x16x32_bf16 v[100:103], v[156:159], v[196:199], v[100:103]
	v_mfma_f32_16x16x32_bf16 v[100:103], v[160:163], v[200:203], v[100:103]
	v_mfma_f32_16x16x32_bf16 v[84:87], v[156:159], v[204:207], v[84:87]
	v_mfma_f32_16x16x32_bf16 v[84:87], v[160:163], v[208:211], v[84:87]
	v_mfma_f32_16x16x32_bf16 v[80:83], v[164:167], v[204:207], v[80:83]
	v_mfma_f32_16x16x32_bf16 v[80:83], v[168:171], v[208:211], v[80:83]
	v_mfma_f32_16x16x32_bf16 v[64:67], v[164:167], v[212:215], v[64:67]
	v_mfma_f32_16x16x32_bf16 v[64:67], v[168:171], v[216:219], v[64:67]
	v_mfma_f32_16x16x32_bf16 v[68:71], v[156:159], v[212:215], v[68:71]
	v_mfma_f32_16x16x32_bf16 v[68:71], v[160:163], v[216:219], v[68:71]
	v_mfma_f32_16x16x32_bf16 v[124:127], v[172:175], v[188:191], v[124:127]
	v_mfma_f32_16x16x32_bf16 v[124:127], v[176:179], v[192:195], v[124:127]
	v_mfma_f32_16x16x32_bf16 v[120:123], v[180:183], v[188:191], v[120:123]
	v_mfma_f32_16x16x32_bf16 v[120:123], v[184:187], v[192:195], v[120:123]
	v_mfma_f32_16x16x32_bf16 v[104:107], v[180:183], v[196:199], v[104:107]
	v_mfma_f32_16x16x32_bf16 v[104:107], v[184:187], v[200:203], v[104:107]
	v_mfma_f32_16x16x32_bf16 v[108:111], v[172:175], v[196:199], v[108:111]
	v_mfma_f32_16x16x32_bf16 v[108:111], v[176:179], v[200:203], v[108:111]
	v_mfma_f32_16x16x32_bf16 v[92:95], v[172:175], v[204:207], v[92:95]
	v_mfma_f32_16x16x32_bf16 v[92:95], v[176:179], v[208:211], v[92:95]
	v_mfma_f32_16x16x32_bf16 v[88:91], v[180:183], v[204:207], v[88:91]
	v_mfma_f32_16x16x32_bf16 v[88:91], v[184:187], v[208:211], v[88:91]
	v_mfma_f32_16x16x32_bf16 v[72:75], v[180:183], v[212:215], v[72:75]
	v_mfma_f32_16x16x32_bf16 v[72:75], v[184:187], v[216:219], v[72:75]
	v_mfma_f32_16x16x32_bf16 v[76:79], v[172:175], v[212:215], v[76:79]
	v_mfma_f32_16x16x32_bf16 v[76:79], v[176:179], v[216:219], v[76:79]
	s_barrier
	s_add_i32 s54, s46, s36
	s_mov_b32 m0, s54
	ds_read_b128 v[188:191], v153 offset:16384
	ds_read_b128 v[192:195], v153 offset:17408
	ds_read_b128 v[196:199], v153 offset:18432
	ds_read_b128 v[200:203], v153 offset:19456
	ds_read_b128 v[204:207], v153 offset:20480
	ds_read_b128 v[208:211], v153 offset:21504
	ds_read_b128 v[212:215], v153 offset:22528
	ds_read_b128 v[216:219], v153 offset:23552
	global_load_lds_dwordx4 v134, s[28:29]
	s_add_i32 m0, s54, 0x2000
	s_add_u32 s54, s28, 0x80000
	s_addc_u32 s55, s29, 0
	s_add_i32 s56, s47, s36
	global_load_lds_dwordx4 v130, s[28:29]
	s_mov_b32 m0, s56
	s_nop 0
	global_load_lds_dwordx4 v134, s[54:55]
	s_add_i32 m0, s56, 0x2000
	s_nop 0
	global_load_lds_dwordx4 v130, s[54:55]
	s_mov_b32 m0, s25
	s_nop 0
	global_load_lds_dwordx4 v136, s[30:31]
	s_mov_b32 m0, s39
	s_nop 0
	global_load_lds_dwordx4 v132, s[30:31]
	s_waitcnt vmcnt(8)
	s_waitcnt lgkmcnt(0)
	s_barrier
	s_waitcnt lgkmcnt(0)
	v_mfma_f32_16x16x32_bf16 v[52:55], v[156:159], v[188:191], v[52:55]
	v_mfma_f32_16x16x32_bf16 v[52:55], v[160:163], v[192:195], v[52:55]
	v_mfma_f32_16x16x32_bf16 v[48:51], v[164:167], v[188:191], v[48:51]
	v_mfma_f32_16x16x32_bf16 v[48:51], v[168:171], v[192:195], v[48:51]
	v_mfma_f32_16x16x32_bf16 v[32:35], v[164:167], v[196:199], v[32:35]
	v_mfma_f32_16x16x32_bf16 v[32:35], v[168:171], v[200:203], v[32:35]
	v_mfma_f32_16x16x32_bf16 v[36:39], v[156:159], v[196:199], v[36:39]
	v_mfma_f32_16x16x32_bf16 v[36:39], v[160:163], v[200:203], v[36:39]
	v_mfma_f32_16x16x32_bf16 v[20:23], v[156:159], v[204:207], v[20:23]
	v_mfma_f32_16x16x32_bf16 v[20:23], v[160:163], v[208:211], v[20:23]
	v_mfma_f32_16x16x32_bf16 v[16:19], v[164:167], v[204:207], v[16:19]
	v_mfma_f32_16x16x32_bf16 v[16:19], v[168:171], v[208:211], v[16:19]
	v_mfma_f32_16x16x32_bf16 v[0:3], v[164:167], v[212:215], v[0:3]
	v_mfma_f32_16x16x32_bf16 v[0:3], v[168:171], v[216:219], v[0:3]
	v_mfma_f32_16x16x32_bf16 v[8:11], v[156:159], v[212:215], v[8:11]
	v_mfma_f32_16x16x32_bf16 v[8:11], v[160:163], v[216:219], v[8:11]
	v_mfma_f32_16x16x32_bf16 v[60:63], v[172:175], v[188:191], v[60:63]
	v_mfma_f32_16x16x32_bf16 v[60:63], v[176:179], v[192:195], v[60:63]
	v_mfma_f32_16x16x32_bf16 v[56:59], v[180:183], v[188:191], v[56:59]
	v_mfma_f32_16x16x32_bf16 v[56:59], v[184:187], v[192:195], v[56:59]
	v_mfma_f32_16x16x32_bf16 v[40:43], v[180:183], v[196:199], v[40:43]
	v_mfma_f32_16x16x32_bf16 v[40:43], v[184:187], v[200:203], v[40:43]
	v_mfma_f32_16x16x32_bf16 v[44:47], v[172:175], v[196:199], v[44:47]
	v_mfma_f32_16x16x32_bf16 v[44:47], v[176:179], v[200:203], v[44:47]
	v_mfma_f32_16x16x32_bf16 v[28:31], v[172:175], v[204:207], v[28:31]
	v_mfma_f32_16x16x32_bf16 v[28:31], v[176:179], v[208:211], v[28:31]
	v_mfma_f32_16x16x32_bf16 v[24:27], v[180:183], v[204:207], v[24:27]
	v_mfma_f32_16x16x32_bf16 v[24:27], v[184:187], v[208:211], v[24:27]
	v_mfma_f32_16x16x32_bf16 v[4:7], v[180:183], v[212:215], v[4:7]
	v_mfma_f32_16x16x32_bf16 v[4:7], v[184:187], v[216:219], v[4:7]
	v_mfma_f32_16x16x32_bf16 v[12:15], v[172:175], v[212:215], v[12:15]
	v_mfma_f32_16x16x32_bf16 v[12:15], v[176:179], v[216:219], v[12:15]
	s_barrier
	s_add_i32 s54, 0, 0x18000
	v_add_u32_e32 v155, s54, v149
	s_add_i32 s55, 0, 0x1c000
	ds_read_b128 v[156:159], v155
	ds_read_b128 v[160:163], v155 offset:1024
	ds_read_b128 v[164:167], v155 offset:2048
	ds_read_b128 v[168:171], v155 offset:3072
	v_add_u32_e32 v155, s55, v149
	ds_read_b128 v[172:175], v155
	ds_read_b128 v[176:179], v155 offset:1024
	ds_read_b128 v[180:183], v155 offset:2048
	ds_read_b128 v[184:187], v155 offset:3072
	s_add_u32 s30, s30, 0x80000
	s_addc_u32 s31, s31, 0
	s_mov_b32 m0, s40
	ds_read_b128 v[188:191], v153 offset:32768
	ds_read_b128 v[192:195], v153 offset:33792
	ds_read_b128 v[196:199], v153 offset:34816
	ds_read_b128 v[200:203], v153 offset:35840
	ds_read_b128 v[204:207], v153 offset:36864
	ds_read_b128 v[208:211], v153 offset:37888
	ds_read_b128 v[212:215], v153 offset:38912
	ds_read_b128 v[216:219], v153 offset:39936
	global_load_lds_dwordx4 v136, s[30:31]
	s_mov_b32 m0, s41
	s_nop 0
	global_load_lds_dwordx4 v132, s[30:31]
	s_waitcnt vmcnt(8)
	s_waitcnt lgkmcnt(0)
	s_barrier
	s_waitcnt lgkmcnt(0)
	v_mfma_f32_16x16x32_bf16 v[116:119], v[156:159], v[188:191], v[116:119]
	v_mfma_f32_16x16x32_bf16 v[116:119], v[160:163], v[192:195], v[116:119]
	v_mfma_f32_16x16x32_bf16 v[112:115], v[164:167], v[188:191], v[112:115]
	v_mfma_f32_16x16x32_bf16 v[112:115], v[168:171], v[192:195], v[112:115]
	v_mfma_f32_16x16x32_bf16 v[96:99], v[164:167], v[196:199], v[96:99]
	v_mfma_f32_16x16x32_bf16 v[96:99], v[168:171], v[200:203], v[96:99]
	v_mfma_f32_16x16x32_bf16 v[100:103], v[156:159], v[196:199], v[100:103]
	v_mfma_f32_16x16x32_bf16 v[100:103], v[160:163], v[200:203], v[100:103]
	v_mfma_f32_16x16x32_bf16 v[84:87], v[156:159], v[204:207], v[84:87]
	v_mfma_f32_16x16x32_bf16 v[84:87], v[160:163], v[208:211], v[84:87]
	v_mfma_f32_16x16x32_bf16 v[80:83], v[164:167], v[204:207], v[80:83]
	v_mfma_f32_16x16x32_bf16 v[80:83], v[168:171], v[208:211], v[80:83]
	v_mfma_f32_16x16x32_bf16 v[64:67], v[164:167], v[212:215], v[64:67]
	v_mfma_f32_16x16x32_bf16 v[64:67], v[168:171], v[216:219], v[64:67]
	v_mfma_f32_16x16x32_bf16 v[68:71], v[156:159], v[212:215], v[68:71]
	v_mfma_f32_16x16x32_bf16 v[68:71], v[160:163], v[216:219], v[68:71]
	v_mfma_f32_16x16x32_bf16 v[124:127], v[172:175], v[188:191], v[124:127]
	v_mfma_f32_16x16x32_bf16 v[124:127], v[176:179], v[192:195], v[124:127]
	v_mfma_f32_16x16x32_bf16 v[120:123], v[180:183], v[188:191], v[120:123]
	v_mfma_f32_16x16x32_bf16 v[120:123], v[184:187], v[192:195], v[120:123]
	v_mfma_f32_16x16x32_bf16 v[104:107], v[180:183], v[196:199], v[104:107]
	v_mfma_f32_16x16x32_bf16 v[104:107], v[184:187], v[200:203], v[104:107]
	v_mfma_f32_16x16x32_bf16 v[108:111], v[172:175], v[196:199], v[108:111]
	v_mfma_f32_16x16x32_bf16 v[108:111], v[176:179], v[200:203], v[108:111]
	v_mfma_f32_16x16x32_bf16 v[92:95], v[172:175], v[204:207], v[92:95]
	v_mfma_f32_16x16x32_bf16 v[92:95], v[176:179], v[208:211], v[92:95]
	v_mfma_f32_16x16x32_bf16 v[88:91], v[180:183], v[204:207], v[88:91]
	v_mfma_f32_16x16x32_bf16 v[88:91], v[184:187], v[208:211], v[88:91]
	v_mfma_f32_16x16x32_bf16 v[72:75], v[180:183], v[212:215], v[72:75]
	v_mfma_f32_16x16x32_bf16 v[72:75], v[184:187], v[216:219], v[72:75]
	v_mfma_f32_16x16x32_bf16 v[76:79], v[172:175], v[212:215], v[76:79]
	v_mfma_f32_16x16x32_bf16 v[76:79], v[176:179], v[216:219], v[76:79]
	s_barrier
	s_add_i32 s30, s54, s36
	s_add_u32 s98, s28, 0x80
	s_addc_u32 s99, s29, 0
	s_mov_b32 m0, s30
	ds_read_b128 v[188:191], v153 offset:49152
	ds_read_b128 v[192:195], v153 offset:50176
	ds_read_b128 v[196:199], v153 offset:51200
	ds_read_b128 v[200:203], v153 offset:52224
	ds_read_b128 v[204:207], v153 offset:53248
	ds_read_b128 v[208:211], v153 offset:54272
	ds_read_b128 v[212:215], v153 offset:55296
	ds_read_b128 v[216:219], v153 offset:56320
	global_load_lds_dwordx4 v134, s[98:99]
	s_add_i32 m0, s30, 0x2000
	s_add_u32 s28, s28, 0x80080
	s_addc_u32 s29, s29, 0
	s_add_i32 s30, s55, s36
	global_load_lds_dwordx4 v130, s[98:99]
	s_mov_b32 m0, s30
	s_nop 0
	global_load_lds_dwordx4 v134, s[28:29]
	s_add_i32 m0, s30, 0x2000
	s_nop 0
	global_load_lds_dwordx4 v130, s[28:29]
	s_mov_b32 m0, s43
	s_nop 0
	global_load_lds_dwordx4 v136, s[100:101]
	s_mov_b32 m0, s44
	s_nop 0
	global_load_lds_dwordx4 v132, s[100:101]
	s_waitcnt vmcnt(8)
	s_waitcnt lgkmcnt(0)
	s_barrier
	s_waitcnt lgkmcnt(0)
	v_mfma_f32_16x16x32_bf16 v[52:55], v[156:159], v[188:191], v[52:55]
	v_mfma_f32_16x16x32_bf16 v[52:55], v[160:163], v[192:195], v[52:55]
	v_mfma_f32_16x16x32_bf16 v[48:51], v[164:167], v[188:191], v[48:51]
	v_mfma_f32_16x16x32_bf16 v[48:51], v[168:171], v[192:195], v[48:51]
	v_mfma_f32_16x16x32_bf16 v[32:35], v[164:167], v[196:199], v[32:35]
	v_mfma_f32_16x16x32_bf16 v[32:35], v[168:171], v[200:203], v[32:35]
	v_mfma_f32_16x16x32_bf16 v[36:39], v[156:159], v[196:199], v[36:39]
	v_mfma_f32_16x16x32_bf16 v[36:39], v[160:163], v[200:203], v[36:39]
	v_mfma_f32_16x16x32_bf16 v[20:23], v[156:159], v[204:207], v[20:23]
	v_mfma_f32_16x16x32_bf16 v[20:23], v[160:163], v[208:211], v[20:23]
	v_mfma_f32_16x16x32_bf16 v[16:19], v[164:167], v[204:207], v[16:19]
	v_mfma_f32_16x16x32_bf16 v[16:19], v[168:171], v[208:211], v[16:19]
	v_mfma_f32_16x16x32_bf16 v[0:3], v[164:167], v[212:215], v[0:3]
	v_mfma_f32_16x16x32_bf16 v[0:3], v[168:171], v[216:219], v[0:3]
	v_mfma_f32_16x16x32_bf16 v[8:11], v[156:159], v[212:215], v[8:11]
	v_mfma_f32_16x16x32_bf16 v[8:11], v[160:163], v[216:219], v[8:11]
	v_mfma_f32_16x16x32_bf16 v[60:63], v[172:175], v[188:191], v[60:63]
	v_mfma_f32_16x16x32_bf16 v[60:63], v[176:179], v[192:195], v[60:63]
	v_mfma_f32_16x16x32_bf16 v[56:59], v[180:183], v[188:191], v[56:59]
	v_mfma_f32_16x16x32_bf16 v[56:59], v[184:187], v[192:195], v[56:59]
	v_mfma_f32_16x16x32_bf16 v[40:43], v[180:183], v[196:199], v[40:43]
	v_mfma_f32_16x16x32_bf16 v[40:43], v[184:187], v[200:203], v[40:43]
	v_mfma_f32_16x16x32_bf16 v[44:47], v[172:175], v[196:199], v[44:47]
	v_mfma_f32_16x16x32_bf16 v[44:47], v[176:179], v[200:203], v[44:47]
	v_mfma_f32_16x16x32_bf16 v[28:31], v[172:175], v[204:207], v[28:31]
	v_mfma_f32_16x16x32_bf16 v[28:31], v[176:179], v[208:211], v[28:31]
	v_mfma_f32_16x16x32_bf16 v[24:27], v[180:183], v[204:207], v[24:27]
	v_mfma_f32_16x16x32_bf16 v[24:27], v[184:187], v[208:211], v[24:27]
	v_mfma_f32_16x16x32_bf16 v[4:7], v[180:183], v[212:215], v[4:7]
	v_mfma_f32_16x16x32_bf16 v[4:7], v[184:187], v[216:219], v[4:7]
	v_mfma_f32_16x16x32_bf16 v[12:15], v[172:175], v[212:215], v[12:15]
	v_mfma_f32_16x16x32_bf16 v[12:15], v[176:179], v[216:219], v[12:15]
	s_barrier
	s_add_i32 s53, s53, 2
	s_add_u32 s26, s26, 0x100
	s_addc_u32 s27, s27, 0
	s_add_u32 s51, s51, 0x100
	s_addc_u32 s52, s52, 0
	s_cmp_gt_u32 s53, 29
	s_cbranch_scc0 .LBB0_671
	v_and_b32_e32 v146, 15, v148
	v_lshrrev_b32_e32 v147, 6, v148
	v_lshl_or_b32 v147, v147, 4, v146
	v_lshlrev_b32_e32 v147, 6, v147
	v_add_u32_e32 v147, 0x20000, v147
	ds_read_b128 v[156:159], v147
	ds_read_b128 v[160:163], v147 offset:16
	ds_read_b128 v[164:167], v147 offset:32
	ds_read_b128 v[168:171], v147 offset:48
	v_lshl_add_u32 v146, s24, 8, v148
	v_mul_u32_u24_e32 v155, 0x2c00, v146
	v_lshl_or_b32 v255, s2, 7, v150
	v_lshl_add_u32 v155, v255, 1, v155
	v_pk_mul_f32 v[124:125], v[116:117], v[124:125]
	v_pk_mul_f32 v[126:127], v[118:119], v[126:127]
	v_pk_mul_f32 v[120:121], v[112:113], v[120:121]
	v_pk_mul_f32 v[122:123], v[114:115], v[122:123]
	v_pk_mul_f32 v[108:109], v[100:101], v[108:109]
	v_pk_mul_f32 v[110:111], v[102:103], v[110:111]
	v_pk_mul_f32 v[104:105], v[96:97], v[104:105]
	v_pk_mul_f32 v[106:107], v[98:99], v[106:107]
	v_pk_mul_f32 v[92:93], v[84:85], v[92:93]
	v_pk_mul_f32 v[94:95], v[86:87], v[94:95]
	v_pk_mul_f32 v[88:89], v[80:81], v[88:89]
	v_pk_mul_f32 v[90:91], v[82:83], v[90:91]
	v_pk_mul_f32 v[76:77], v[68:69], v[76:77]
	v_pk_mul_f32 v[78:79], v[70:71], v[78:79]
	v_pk_mul_f32 v[72:73], v[64:65], v[72:73]
	v_pk_mul_f32 v[74:75], v[66:67], v[74:75]
	v_pk_mul_f32 v[60:61], v[52:53], v[60:61]
	v_pk_mul_f32 v[62:63], v[54:55], v[62:63]
	v_pk_mul_f32 v[56:57], v[48:49], v[56:57]
	v_pk_mul_f32 v[58:59], v[50:51], v[58:59]
	v_pk_mul_f32 v[44:45], v[36:37], v[44:45]
	v_pk_mul_f32 v[46:47], v[38:39], v[46:47]
	v_pk_mul_f32 v[40:41], v[32:33], v[40:41]
	v_pk_mul_f32 v[42:43], v[34:35], v[42:43]
	v_pk_mul_f32 v[28:29], v[20:21], v[28:29]
	v_pk_mul_f32 v[30:31], v[22:23], v[30:31]
	v_pk_mul_f32 v[24:25], v[16:17], v[24:25]
	v_pk_mul_f32 v[26:27], v[18:19], v[26:27]
	v_pk_mul_f32 v[12:13], v[8:9], v[12:13]
	v_pk_mul_f32 v[14:15], v[10:11], v[14:15]
	v_pk_mul_f32 v[4:5], v[0:1], v[4:5]
	v_pk_mul_f32 v[6:7], v[2:3], v[6:7]
	s_and_b64 vcc, exec, s[14:15]
	s_cbranch_vccz .LBB0_674
	s_barrier
.LBB0_674:
	s_andn2_b64 vcc, exec, s[0:1]
	s_mov_b64 s[0:1], -1
	s_waitcnt lgkmcnt(0)
	v_mov_b32_e32 v147, v155
	v_pk_mul_f32 v[172:173], v[116:117], v[156:157] op_sel_hi:[1,0]
	v_pk_mul_f32 v[174:175], v[118:119], v[156:157] op_sel_hi:[1,0]
	v_pk_mul_f32 v[176:177], v[112:113], v[156:157] op_sel_hi:[1,0]
	v_pk_mul_f32 v[178:179], v[114:115], v[156:157] op_sel_hi:[1,0]
	v_exp_f32_e32 v172, v172
	v_exp_f32_e32 v173, v173
	v_exp_f32_e32 v174, v174
	v_exp_f32_e32 v175, v175
	v_exp_f32_e32 v176, v176
	v_exp_f32_e32 v177, v177
	v_exp_f32_e32 v178, v178
	v_exp_f32_e32 v179, v179
	v_pk_fma_f32 v[172:173], v[172:173], v[156:157], v[156:157] op_sel:[0,1,1]
	v_pk_fma_f32 v[174:175], v[174:175], v[156:157], v[156:157] op_sel:[0,1,1]
	v_pk_fma_f32 v[176:177], v[176:177], v[156:157], v[156:157] op_sel:[0,1,1]
	v_pk_fma_f32 v[178:179], v[178:179], v[156:157], v[156:157] op_sel:[0,1,1]
	v_rcp_f32_e32 v172, v172
	v_rcp_f32_e32 v173, v173
	v_rcp_f32_e32 v174, v174
	v_rcp_f32_e32 v175, v175
	v_rcp_f32_e32 v176, v176
	v_rcp_f32_e32 v177, v177
	v_rcp_f32_e32 v178, v178
	v_rcp_f32_e32 v179, v179
	v_pk_mul_f32 v[124:125], v[124:125], v[172:173]
	v_pk_mul_f32 v[126:127], v[126:127], v[174:175]
	v_pk_mul_f32 v[120:121], v[120:121], v[176:177]
	v_pk_mul_f32 v[122:123], v[122:123], v[178:179]
	v_cvt_pk_bf16_f32 v112, v124, v125
	v_cvt_pk_bf16_f32 v113, v126, v127
	v_cvt_pk_bf16_f32 v114, v120, v121
	v_cvt_pk_bf16_f32 v115, v122, v123
	global_store_dwordx4 v147, v[112:115], s[8:9]
	v_add_u32_e32 v147, 0x2c000, v155
	v_pk_mul_f32 v[172:173], v[100:101], v[158:159] op_sel_hi:[1,0]
	v_pk_mul_f32 v[174:175], v[102:103], v[158:159] op_sel_hi:[1,0]
	v_pk_mul_f32 v[176:177], v[96:97], v[158:159] op_sel_hi:[1,0]
	v_pk_mul_f32 v[178:179], v[98:99], v[158:159] op_sel_hi:[1,0]
	v_exp_f32_e32 v172, v172
	v_exp_f32_e32 v173, v173
	v_exp_f32_e32 v174, v174
	v_exp_f32_e32 v175, v175
	v_exp_f32_e32 v176, v176
	v_exp_f32_e32 v177, v177
	v_exp_f32_e32 v178, v178
	v_exp_f32_e32 v179, v179
	v_pk_fma_f32 v[172:173], v[172:173], v[158:159], v[158:159] op_sel:[0,1,1]
	v_pk_fma_f32 v[174:175], v[174:175], v[158:159], v[158:159] op_sel:[0,1,1]
	v_pk_fma_f32 v[176:177], v[176:177], v[158:159], v[158:159] op_sel:[0,1,1]
	v_pk_fma_f32 v[178:179], v[178:179], v[158:159], v[158:159] op_sel:[0,1,1]
	v_rcp_f32_e32 v172, v172
	v_rcp_f32_e32 v173, v173
	v_rcp_f32_e32 v174, v174
	v_rcp_f32_e32 v175, v175
	v_rcp_f32_e32 v176, v176
	v_rcp_f32_e32 v177, v177
	v_rcp_f32_e32 v178, v178
	v_rcp_f32_e32 v179, v179
	v_pk_mul_f32 v[108:109], v[108:109], v[172:173]
	v_pk_mul_f32 v[110:111], v[110:111], v[174:175]
	v_pk_mul_f32 v[104:105], v[104:105], v[176:177]
	v_pk_mul_f32 v[106:107], v[106:107], v[178:179]
	v_cvt_pk_bf16_f32 v96, v108, v109
	v_cvt_pk_bf16_f32 v97, v110, v111
	v_cvt_pk_bf16_f32 v98, v104, v105
	v_cvt_pk_bf16_f32 v99, v106, v107
	global_store_dwordx4 v147, v[96:99], s[8:9]
	v_add_u32_e32 v147, 0x58000, v155
	v_pk_mul_f32 v[172:173], v[84:85], v[160:161] op_sel_hi:[1,0]
	v_pk_mul_f32 v[174:175], v[86:87], v[160:161] op_sel_hi:[1,0]
	v_pk_mul_f32 v[176:177], v[80:81], v[160:161] op_sel_hi:[1,0]
	v_pk_mul_f32 v[178:179], v[82:83], v[160:161] op_sel_hi:[1,0]
	v_exp_f32_e32 v172, v172
	v_exp_f32_e32 v173, v173
	v_exp_f32_e32 v174, v174
	v_exp_f32_e32 v175, v175
	v_exp_f32_e32 v176, v176
	v_exp_f32_e32 v177, v177
	v_exp_f32_e32 v178, v178
	v_exp_f32_e32 v179, v179
	v_pk_fma_f32 v[172:173], v[172:173], v[160:161], v[160:161] op_sel:[0,1,1]
	v_pk_fma_f32 v[174:175], v[174:175], v[160:161], v[160:161] op_sel:[0,1,1]
	v_pk_fma_f32 v[176:177], v[176:177], v[160:161], v[160:161] op_sel:[0,1,1]
	v_pk_fma_f32 v[178:179], v[178:179], v[160:161], v[160:161] op_sel:[0,1,1]
	v_rcp_f32_e32 v172, v172
	v_rcp_f32_e32 v173, v173
	v_rcp_f32_e32 v174, v174
	v_rcp_f32_e32 v175, v175
	v_rcp_f32_e32 v176, v176
	v_rcp_f32_e32 v177, v177
	v_rcp_f32_e32 v178, v178
	v_rcp_f32_e32 v179, v179
	v_pk_mul_f32 v[92:93], v[92:93], v[172:173]
	v_pk_mul_f32 v[94:95], v[94:95], v[174:175]
	v_pk_mul_f32 v[88:89], v[88:89], v[176:177]
	v_pk_mul_f32 v[90:91], v[90:91], v[178:179]
	v_cvt_pk_bf16_f32 v80, v92, v93
	v_cvt_pk_bf16_f32 v81, v94, v95
	v_cvt_pk_bf16_f32 v82, v88, v89
	v_cvt_pk_bf16_f32 v83, v90, v91
	global_store_dwordx4 v147, v[80:83], s[8:9]
	v_add_u32_e32 v147, 0x84000, v155
	v_pk_mul_f32 v[172:173], v[68:69], v[162:163] op_sel_hi:[1,0]
	v_pk_mul_f32 v[174:175], v[70:71], v[162:163] op_sel_hi:[1,0]
	v_pk_mul_f32 v[176:177], v[64:65], v[162:163] op_sel_hi:[1,0]
	v_pk_mul_f32 v[178:179], v[66:67], v[162:163] op_sel_hi:[1,0]
	v_exp_f32_e32 v172, v172
	v_exp_f32_e32 v173, v173
	v_exp_f32_e32 v174, v174
	v_exp_f32_e32 v175, v175
	v_exp_f32_e32 v176, v176
	v_exp_f32_e32 v177, v177
	v_exp_f32_e32 v178, v178
	v_exp_f32_e32 v179, v179
	v_pk_fma_f32 v[172:173], v[172:173], v[162:163], v[162:163] op_sel:[0,1,1]
	v_pk_fma_f32 v[174:175], v[174:175], v[162:163], v[162:163] op_sel:[0,1,1]
	v_pk_fma_f32 v[176:177], v[176:177], v[162:163], v[162:163] op_sel:[0,1,1]
	v_pk_fma_f32 v[178:179], v[178:179], v[162:163], v[162:163] op_sel:[0,1,1]
	v_rcp_f32_e32 v172, v172
	v_rcp_f32_e32 v173, v173
	v_rcp_f32_e32 v174, v174
	v_rcp_f32_e32 v175, v175
	v_rcp_f32_e32 v176, v176
	v_rcp_f32_e32 v177, v177
	v_rcp_f32_e32 v178, v178
	v_rcp_f32_e32 v179, v179
	v_pk_mul_f32 v[76:77], v[76:77], v[172:173]
	v_pk_mul_f32 v[78:79], v[78:79], v[174:175]
	v_pk_mul_f32 v[72:73], v[72:73], v[176:177]
	v_pk_mul_f32 v[74:75], v[74:75], v[178:179]
	v_cvt_pk_bf16_f32 v64, v76, v77
	v_cvt_pk_bf16_f32 v65, v78, v79
	v_cvt_pk_bf16_f32 v66, v72, v73
	v_cvt_pk_bf16_f32 v67, v74, v75
	global_store_dwordx4 v147, v[64:67], s[8:9]
	v_add_u32_e32 v147, 0x160000, v155
	v_pk_mul_f32 v[172:173], v[52:53], v[164:165] op_sel_hi:[1,0]
	v_pk_mul_f32 v[174:175], v[54:55], v[164:165] op_sel_hi:[1,0]
	v_pk_mul_f32 v[176:177], v[48:49], v[164:165] op_sel_hi:[1,0]
	v_pk_mul_f32 v[178:179], v[50:51], v[164:165] op_sel_hi:[1,0]
	v_exp_f32_e32 v172, v172
	v_exp_f32_e32 v173, v173
	v_exp_f32_e32 v174, v174
	v_exp_f32_e32 v175, v175
	v_exp_f32_e32 v176, v176
	v_exp_f32_e32 v177, v177
	v_exp_f32_e32 v178, v178
	v_exp_f32_e32 v179, v179
	v_pk_fma_f32 v[172:173], v[172:173], v[164:165], v[164:165] op_sel:[0,1,1]
	v_pk_fma_f32 v[174:175], v[174:175], v[164:165], v[164:165] op_sel:[0,1,1]
	v_pk_fma_f32 v[176:177], v[176:177], v[164:165], v[164:165] op_sel:[0,1,1]
	v_pk_fma_f32 v[178:179], v[178:179], v[164:165], v[164:165] op_sel:[0,1,1]
	v_rcp_f32_e32 v172, v172
	v_rcp_f32_e32 v173, v173
	v_rcp_f32_e32 v174, v174
	v_rcp_f32_e32 v175, v175
	v_rcp_f32_e32 v176, v176
	v_rcp_f32_e32 v177, v177
	v_rcp_f32_e32 v178, v178
	v_rcp_f32_e32 v179, v179
	v_pk_mul_f32 v[60:61], v[60:61], v[172:173]
	v_pk_mul_f32 v[62:63], v[62:63], v[174:175]
	v_pk_mul_f32 v[56:57], v[56:57], v[176:177]
	v_pk_mul_f32 v[58:59], v[58:59], v[178:179]
	v_cvt_pk_bf16_f32 v48, v60, v61
	v_cvt_pk_bf16_f32 v49, v62, v63
	v_cvt_pk_bf16_f32 v50, v56, v57
	v_cvt_pk_bf16_f32 v51, v58, v59
	global_store_dwordx4 v147, v[48:51], s[8:9]
	v_add_u32_e32 v147, 0x18c000, v155
	v_pk_mul_f32 v[172:173], v[36:37], v[166:167] op_sel_hi:[1,0]
	v_pk_mul_f32 v[174:175], v[38:39], v[166:167] op_sel_hi:[1,0]
	v_pk_mul_f32 v[176:177], v[32:33], v[166:167] op_sel_hi:[1,0]
	v_pk_mul_f32 v[178:179], v[34:35], v[166:167] op_sel_hi:[1,0]
	v_exp_f32_e32 v172, v172
	v_exp_f32_e32 v173, v173
	v_exp_f32_e32 v174, v174
	v_exp_f32_e32 v175, v175
	v_exp_f32_e32 v176, v176
	v_exp_f32_e32 v177, v177
	v_exp_f32_e32 v178, v178
	v_exp_f32_e32 v179, v179
	v_pk_fma_f32 v[172:173], v[172:173], v[166:167], v[166:167] op_sel:[0,1,1]
	v_pk_fma_f32 v[174:175], v[174:175], v[166:167], v[166:167] op_sel:[0,1,1]
	v_pk_fma_f32 v[176:177], v[176:177], v[166:167], v[166:167] op_sel:[0,1,1]
	v_pk_fma_f32 v[178:179], v[178:179], v[166:167], v[166:167] op_sel:[0,1,1]
	v_rcp_f32_e32 v172, v172
	v_rcp_f32_e32 v173, v173
	v_rcp_f32_e32 v174, v174
	v_rcp_f32_e32 v175, v175
	v_rcp_f32_e32 v176, v176
	v_rcp_f32_e32 v177, v177
	v_rcp_f32_e32 v178, v178
	v_rcp_f32_e32 v179, v179
	v_pk_mul_f32 v[44:45], v[44:45], v[172:173]
	v_pk_mul_f32 v[46:47], v[46:47], v[174:175]
	v_pk_mul_f32 v[40:41], v[40:41], v[176:177]
	v_pk_mul_f32 v[42:43], v[42:43], v[178:179]
	v_cvt_pk_bf16_f32 v32, v44, v45
	v_cvt_pk_bf16_f32 v33, v46, v47
	v_cvt_pk_bf16_f32 v34, v40, v41
	v_cvt_pk_bf16_f32 v35, v42, v43
	global_store_dwordx4 v147, v[32:35], s[8:9]
	v_add_u32_e32 v147, 0x1b8000, v155
	v_pk_mul_f32 v[172:173], v[20:21], v[168:169] op_sel_hi:[1,0]
	v_pk_mul_f32 v[174:175], v[22:23], v[168:169] op_sel_hi:[1,0]
	v_pk_mul_f32 v[176:177], v[16:17], v[168:169] op_sel_hi:[1,0]
	v_pk_mul_f32 v[178:179], v[18:19], v[168:169] op_sel_hi:[1,0]
	v_exp_f32_e32 v172, v172
	v_exp_f32_e32 v173, v173
	v_exp_f32_e32 v174, v174
	v_exp_f32_e32 v175, v175
	v_exp_f32_e32 v176, v176
	v_exp_f32_e32 v177, v177
	v_exp_f32_e32 v178, v178
	v_exp_f32_e32 v179, v179
	v_pk_fma_f32 v[172:173], v[172:173], v[168:169], v[168:169] op_sel:[0,1,1]
	v_pk_fma_f32 v[174:175], v[174:175], v[168:169], v[168:169] op_sel:[0,1,1]
	v_pk_fma_f32 v[176:177], v[176:177], v[168:169], v[168:169] op_sel:[0,1,1]
	v_pk_fma_f32 v[178:179], v[178:179], v[168:169], v[168:169] op_sel:[0,1,1]
	v_rcp_f32_e32 v172, v172
	v_rcp_f32_e32 v173, v173
	v_rcp_f32_e32 v174, v174
	v_rcp_f32_e32 v175, v175
	v_rcp_f32_e32 v176, v176
	v_rcp_f32_e32 v177, v177
	v_rcp_f32_e32 v178, v178
	v_rcp_f32_e32 v179, v179
	v_pk_mul_f32 v[28:29], v[28:29], v[172:173]
	v_pk_mul_f32 v[30:31], v[30:31], v[174:175]
	v_pk_mul_f32 v[24:25], v[24:25], v[176:177]
	v_pk_mul_f32 v[26:27], v[26:27], v[178:179]
	v_cvt_pk_bf16_f32 v16, v28, v29
	v_cvt_pk_bf16_f32 v17, v30, v31
	v_cvt_pk_bf16_f32 v18, v24, v25
	v_cvt_pk_bf16_f32 v19, v26, v27
	global_store_dwordx4 v147, v[16:19], s[8:9]
	v_add_u32_e32 v147, 0x1e4000, v155
	v_pk_mul_f32 v[172:173], v[8:9], v[170:171] op_sel_hi:[1,0]
	v_pk_mul_f32 v[174:175], v[10:11], v[170:171] op_sel_hi:[1,0]
	v_pk_mul_f32 v[176:177], v[0:1], v[170:171] op_sel_hi:[1,0]
	v_pk_mul_f32 v[178:179], v[2:3], v[170:171] op_sel_hi:[1,0]
	v_exp_f32_e32 v172, v172
	v_exp_f32_e32 v173, v173
	v_exp_f32_e32 v174, v174
	v_exp_f32_e32 v175, v175
	v_exp_f32_e32 v176, v176
	v_exp_f32_e32 v177, v177
	v_exp_f32_e32 v178, v178
	v_exp_f32_e32 v179, v179
	v_pk_fma_f32 v[172:173], v[172:173], v[170:171], v[170:171] op_sel:[0,1,1]
	v_pk_fma_f32 v[174:175], v[174:175], v[170:171], v[170:171] op_sel:[0,1,1]
	v_pk_fma_f32 v[176:177], v[176:177], v[170:171], v[170:171] op_sel:[0,1,1]
	v_pk_fma_f32 v[178:179], v[178:179], v[170:171], v[170:171] op_sel:[0,1,1]
	v_rcp_f32_e32 v172, v172
	v_rcp_f32_e32 v173, v173
	v_rcp_f32_e32 v174, v174
	v_rcp_f32_e32 v175, v175
	v_rcp_f32_e32 v176, v176
	v_rcp_f32_e32 v177, v177
	v_rcp_f32_e32 v178, v178
	v_rcp_f32_e32 v179, v179
	v_pk_mul_f32 v[12:13], v[12:13], v[172:173]
	v_pk_mul_f32 v[14:15], v[14:15], v[174:175]
	v_pk_mul_f32 v[4:5], v[4:5], v[176:177]
	v_pk_mul_f32 v[6:7], v[6:7], v[178:179]
	v_cvt_pk_bf16_f32 v0, v12, v13
	v_cvt_pk_bf16_f32 v1, v14, v15
	v_cvt_pk_bf16_f32 v2, v4, v5
	v_cvt_pk_bf16_f32 v3, v6, v7
	global_store_dwordx4 v147, v[0:3], s[8:9]
	s_cbranch_vccnz .LBB0_667
	s_andn2_b64 vcc, exec, s[6:7]
	s_cbranch_vccnz .LBB0_666
	s_barrier
	s_branch .LBB0_666
